# xattn units remapped so each XCD works on its own GEMM row tiles; seam 8 XCD-local
# speedup vs baseline: 1.0616x; 1.0030x over previous
.LBB0_1947:
	v_readlane_b32 s4, v244, 47
	s_cmp_lt_i32 s4, 10
	s_cselect_b64 s[2:3], -1, 0
	s_and_b64 s[2:3], s[2:3], s[0:1]
	s_cmpk_lt_i32 s69, 0x600
	s_cselect_b64 s[0:1], -1, 0
	s_and_b64 s[0:1], s[2:3], s[0:1]
	s_andn2_b64 vcc, exec, s[0:1]
	v_readlane_b32 s5, v244, 48
	v_readlane_b32 s6, v244, 49
	v_readlane_b32 s7, v244, 50
	s_cbranch_vccnz .LBB0_1956
	v_and_b32_e32 v249, 63, v182
	v_readlane_b32 s4, v244, 6
	v_readlane_b32 s5, v244, 7
	v_readlane_b32 s6, v244, 39
	v_readlane_b32 s7, v244, 40
	v_readlane_b32 s8, v244, 41
	v_readlane_b32 s9, v244, 42
	v_lshlrev_b32_e32 v242, 2, v249
	s_nop 3
	global_load_dword v216, v242, s[6:7] offset:0
	global_load_dword v217, v242, s[6:7] offset:256
	global_load_dword v218, v242, s[6:7] offset:512
	global_load_dword v219, v242, s[6:7] offset:768
	global_load_dword v220, v242, s[8:9] offset:0
	global_load_dword v221, v242, s[8:9] offset:256
	global_load_dword v222, v242, s[8:9] offset:512
	global_load_dword v223, v242, s[8:9] offset:768
	v_and_b32_e32 v243, 15, v182
	v_bfe_u32 v245, v182, 4, 2
	v_lshl_or_b32 v246, s88, 4, v243
	v_lshlrev_b32_e32 v228, 11, v246
	v_lshl_add_u32 v238, v245, 3, v228
	v_lshl_add_u32 v228, v245, 4, v228
	v_add_u32_e32 v229, 0x40000, v228
	v_add_u32_e32 v239, 0x40000, v238
	v_lshlrev_b32_e32 v230, 4, v246
	v_mul_u32_u24_e32 v231, 528, v243
	v_lshl_add_u32 v232, v245, 3, v231
	v_lshl_add_u32 v231, v245, 4, v231
	v_lshrrev_b32_e32 v243, 5, v182
	v_and_b32_e32 v245, 31, v182
	v_lshlrev_b32_e32 v245, 4, v245
	v_lshl_add_u32 v224, v243, 11, v245
	v_mul_u32_u24_e32 v225, 5120, v243
	v_add_u32_e32 v225, v225, v245
	v_mul_u32_u24_e32 v226, 528, v243
	v_add_u32_e32 v226, v226, v245
	v_add_u32_e32 v227, 67584, v226
	v_and_b32_e32 v250, 3, v243
	v_bfe_u32 v242, v243, 2, 1
	v_lshl_or_b32 v250, v242, 4, v250
	v_bfe_u32 v242, v243, 3, 1
	v_lshl_or_b32 v250, v242, 2, v250
	v_mul_u32_u24_e32 v250, 528, v250
	v_add_u32_e32 v250, v250, v245
	v_add_u32_e32 v251, 67584, v250
	v_xor_b32_e32 v236, 16, v249
	v_lshlrev_b32_e32 v236, 2, v236
	v_xor_b32_e32 v237, 32, v249
	v_lshlrev_b32_e32 v237, 2, v237
	v_mov_b32_e32 v181, 0x358637bd
	s_waitcnt vmcnt(0)
	v_mul_f32_e32 v216, v216, v220
	v_mul_f32_e32 v217, v217, v221
	v_mul_f32_e32 v218, v218, v222
	v_mul_f32_e32 v219, v219, v223
	v_max_f32_e64 v216, |v216|, |v217|
	v_max_f32_e64 v218, |v218|, |v219|
	v_max_f32_e32 v216, v216, v218
	v_xor_b32_e32 v242, 1, v249
	v_lshlrev_b32_e32 v242, 2, v242
	ds_bpermute_b32 v243, v242, v216
	s_waitcnt lgkmcnt(0)
	v_max_f32_e32 v216, v216, v243
	v_xor_b32_e32 v242, 2, v249
	v_lshlrev_b32_e32 v242, 2, v242
	ds_bpermute_b32 v243, v242, v216
	s_waitcnt lgkmcnt(0)
	v_max_f32_e32 v216, v216, v243
	v_xor_b32_e32 v242, 4, v249
	v_lshlrev_b32_e32 v242, 2, v242
	ds_bpermute_b32 v243, v242, v216
	s_waitcnt lgkmcnt(0)
	v_max_f32_e32 v216, v216, v243
	v_xor_b32_e32 v242, 8, v249
	v_lshlrev_b32_e32 v242, 2, v242
	ds_bpermute_b32 v243, v242, v216
	s_waitcnt lgkmcnt(0)
	v_max_f32_e32 v216, v216, v243
	v_xor_b32_e32 v242, 16, v249
	v_lshlrev_b32_e32 v242, 2, v242
	ds_bpermute_b32 v243, v242, v216
	s_waitcnt lgkmcnt(0)
	v_max_f32_e32 v216, v216, v243
	v_xor_b32_e32 v242, 32, v249
	v_lshlrev_b32_e32 v242, 2, v242
	ds_bpermute_b32 v243, v242, v216
	s_waitcnt lgkmcnt(0)
	v_max_f32_e32 v216, v216, v243
	v_mul_f32_e32 v180, 0x41b8aa3b, v216
	s_and_b32 s0, s69, 31
	s_lshr_b32 s1, s69, 8
	s_lshl_b32 s1, s1, 5
	s_add_i32 s1, s1, s0
	s_mul_i32 s0, s1, 2731
	s_lshr_b32 s0, s0, 16
	s_mul_i32 s17, s0, 24
	s_sub_i32 s1, s1, s17
	s_bfe_u32 s17, s69, 0x30005
	s_mul_i32 s17, s17, 24
	s_add_i32 s1, s1, s17
	s_lshl_b32 s11, s1, 19
	s_lshl_b32 s12, s0, 9
	s_add_u32 s11, s11, s12
	s_add_u32 s12, s11, 0xf000000
	s_add_u32 s10, s4, s12
	s_addc_u32 s11, s5, 0
	s_lshl_b32 s12, s1, 12
	s_lshl_b32 s13, s0, 2
	s_add_u32 s12, s12, s13
	s_add_u32 s12, s12, 0x1fa60000
	s_add_u32 s12, s4, s12
	s_addc_u32 s13, s5, 0
	global_load_dwordx4 v[0:3], v228, s[10:11] offset:0
	global_load_dwordx4 v[4:7], v228, s[10:11] offset:64
	global_load_dwordx4 v[8:11], v228, s[10:11] offset:128
	global_load_dwordx4 v[12:15], v228, s[10:11] offset:192
	global_load_dwordx4 v[16:19], v228, s[10:11] offset:256
	global_load_dwordx4 v[20:23], v228, s[10:11] offset:320
	global_load_dwordx4 v[24:27], v228, s[10:11] offset:384
	global_load_dwordx4 v[28:31], v228, s[10:11] offset:448
	global_load_dwordx4 v[32:35], v229, s[10:11] offset:0
	global_load_dwordx4 v[36:39], v229, s[10:11] offset:64
	global_load_dwordx4 v[40:43], v229, s[10:11] offset:128
	global_load_dwordx4 v[44:47], v229, s[10:11] offset:192
	global_load_dwordx4 v[48:51], v229, s[10:11] offset:256
	global_load_dwordx4 v[52:55], v229, s[10:11] offset:320
	global_load_dwordx4 v[56:59], v229, s[10:11] offset:384
	global_load_dwordx4 v[60:63], v229, s[10:11] offset:448
	global_load_dword v247, v230, s[12:13]
	global_load_dword v248, v230, s[12:13] offset:2048
.Lxa_unit:
	s_and_b32 s0, s69, 31
	s_lshr_b32 s1, s69, 8
	s_lshl_b32 s1, s1, 5
	s_add_i32 s1, s1, s0
	s_mul_i32 s0, s1, 2731
	s_lshr_b32 s0, s0, 16
	s_mul_i32 s17, s0, 24
	s_sub_i32 s1, s1, s17
	s_bfe_u32 s17, s69, 0x30005
	s_mul_i32 s17, s17, 24
	s_add_i32 s1, s1, s17
	s_lshr_b32 s10, s1, 5
	s_sub_i32 s11, s1, 64
	s_lshr_b32 s11, s11, 4
	s_add_i32 s11, s11, 2
	s_cmp_lt_u32 s1, 64
	s_cselect_b32 s10, s10, s11
	s_lshl_b32 s11, s10, 19
	s_lshl_b32 s12, s0, 9
	s_add_u32 s11, s11, s12
	s_add_u32 s11, s11, 0x19000000
	s_add_u32 s6, s4, s11
	s_addc_u32 s7, s5, 0
	s_mul_i32 s11, s0, 0x140000
	s_lshl_b32 s12, s10, 9
	s_add_u32 s11, s11, s12
	s_add_u32 s11, s11, 0x19800000
	s_add_u32 s8, s4, s11
	s_addc_u32 s9, s5, 0
	s_lshl_b32 s12, s1, 19
	s_lshl_b32 s13, s0, 9
	s_add_u32 s12, s12, s13
	s_add_u32 s12, s12, 0x9000000
	s_add_u32 s14, s4, s12
	s_addc_u32 s15, s5, 0
	global_load_dwordx4 v[128:131], v224, s[6:7]
	s_add_u32 s6, s6, 0x8000
	s_addc_u32 s7, s7, 0
	global_load_dwordx4 v[132:135], v224, s[6:7]
	s_add_u32 s6, s6, 0x8000
	s_addc_u32 s7, s7, 0
	global_load_dwordx4 v[136:139], v224, s[6:7]
	s_add_u32 s6, s6, 0x8000
	s_addc_u32 s7, s7, 0
	global_load_dwordx4 v[140:143], v224, s[6:7]
	s_add_u32 s6, s6, 0x8000
	s_addc_u32 s7, s7, 0
	global_load_dwordx4 v[144:147], v224, s[6:7]
	s_add_u32 s6, s6, 0x8000
	s_addc_u32 s7, s7, 0
	global_load_dwordx4 v[148:151], v224, s[6:7]
	s_add_u32 s6, s6, 0x8000
	s_addc_u32 s7, s7, 0
	global_load_dwordx4 v[152:155], v224, s[6:7]
	s_add_u32 s6, s6, 0x8000
	s_addc_u32 s7, s7, 0
	global_load_dwordx4 v[156:159], v224, s[6:7]
	s_add_u32 s6, s6, 0x8000
	s_addc_u32 s7, s7, 0
	global_load_dwordx4 v[184:187], v224, s[6:7]
	s_add_u32 s6, s6, 0x8000
	s_addc_u32 s7, s7, 0
	global_load_dwordx4 v[188:191], v224, s[6:7]
	s_add_u32 s6, s6, 0x8000
	s_addc_u32 s7, s7, 0
	global_load_dwordx4 v[192:195], v224, s[6:7]
	s_add_u32 s6, s6, 0x8000
	s_addc_u32 s7, s7, 0
	global_load_dwordx4 v[196:199], v224, s[6:7]
	s_add_u32 s6, s6, 0x8000
	s_addc_u32 s7, s7, 0
	global_load_dwordx4 v[200:203], v224, s[6:7]
	s_add_u32 s6, s6, 0x8000
	s_addc_u32 s7, s7, 0
	global_load_dwordx4 v[204:207], v224, s[6:7]
	s_add_u32 s6, s6, 0x8000
	s_addc_u32 s7, s7, 0
	global_load_dwordx4 v[208:211], v224, s[6:7]
	s_add_u32 s6, s6, 0x8000
	s_addc_u32 s7, s7, 0
	global_load_dwordx4 v[212:215], v224, s[6:7]
	s_waitcnt vmcnt(12)
	ds_write_b128 v226, v[128:131] offset:0
	ds_write_b128 v226, v[132:135] offset:8448
	ds_write_b128 v226, v[136:139] offset:16896
	ds_write_b128 v226, v[140:143] offset:25344
	s_waitcnt vmcnt(8)
	ds_write_b128 v226, v[144:147] offset:33792
	ds_write_b128 v226, v[148:151] offset:42240
	ds_write_b128 v226, v[152:155] offset:50688
	ds_write_b128 v226, v[156:159] offset:59136
	s_waitcnt vmcnt(4)
	ds_write_b128 v227, v[184:187] offset:0
	ds_write_b128 v227, v[188:191] offset:8448
	ds_write_b128 v227, v[192:195] offset:16896
	ds_write_b128 v227, v[196:199] offset:25344
	s_waitcnt vmcnt(0)
	ds_write_b128 v227, v[200:203] offset:33792
	ds_write_b128 v227, v[204:207] offset:42240
	ds_write_b128 v227, v[208:211] offset:50688
	ds_write_b128 v227, v[212:215] offset:59136
	s_waitcnt vmcnt(0)
	v_fmamk_f32 v178, v247, 0x3b800000, v181
	v_fmamk_f32 v179, v248, 0x3b800000, v181
	v_rsq_f32_e32 v178, v178
	v_rsq_f32_e32 v179, v179
	v_mov_b32_e32 v176, 0
	v_mov_b32_e32 v177, 0
	v_mul_f32_e32 v178, 0x3db8aa3b, v178
	v_mul_f32_e32 v179, 0x3db8aa3b, v179
	s_waitcnt lgkmcnt(0)
	s_barrier
	v_mov_b32_e32 v233, v231
	ds_read_b128 v[128:131], v233 offset:0
	ds_read_b128 v[132:135], v233 offset:64
	ds_read_b128 v[136:139], v233 offset:128
	ds_read_b128 v[140:143], v233 offset:192
	ds_read_b128 v[144:147], v233 offset:256
	ds_read_b128 v[148:151], v233 offset:320
	ds_read_b128 v[152:155], v233 offset:384
	ds_read_b128 v[156:159], v233 offset:448
	s_waitcnt lgkmcnt(0)
	ds_read_b128 v[184:187], v233 offset:8448
	ds_read_b128 v[188:191], v233 offset:8512
	ds_read_b128 v[192:195], v233 offset:8576
	ds_read_b128 v[196:199], v233 offset:8640
	ds_read_b128 v[200:203], v233 offset:8704
	ds_read_b128 v[204:207], v233 offset:8768
	ds_read_b128 v[208:211], v233 offset:8832
	ds_read_b128 v[212:215], v233 offset:8896
	v_mfma_f32_16x16x32_bf16 v[160:163], v[128:131], v[0:3], 0
	v_mfma_f32_16x16x32_bf16 v[164:167], v[128:131], v[32:35], 0
	v_mfma_f32_16x16x32_bf16 v[160:163], v[132:135], v[4:7], v[160:163]
	v_mfma_f32_16x16x32_bf16 v[164:167], v[132:135], v[36:39], v[164:167]
	v_mfma_f32_16x16x32_bf16 v[160:163], v[136:139], v[8:11], v[160:163]
	v_mfma_f32_16x16x32_bf16 v[164:167], v[136:139], v[40:43], v[164:167]
	v_mfma_f32_16x16x32_bf16 v[160:163], v[140:143], v[12:15], v[160:163]
	v_mfma_f32_16x16x32_bf16 v[164:167], v[140:143], v[44:47], v[164:167]
	v_mfma_f32_16x16x32_bf16 v[160:163], v[144:147], v[16:19], v[160:163]
	v_mfma_f32_16x16x32_bf16 v[164:167], v[144:147], v[48:51], v[164:167]
	v_mfma_f32_16x16x32_bf16 v[160:163], v[148:151], v[20:23], v[160:163]
	v_mfma_f32_16x16x32_bf16 v[164:167], v[148:151], v[52:55], v[164:167]
	v_mfma_f32_16x16x32_bf16 v[160:163], v[152:155], v[24:27], v[160:163]
	v_mfma_f32_16x16x32_bf16 v[164:167], v[152:155], v[56:59], v[164:167]
	v_mfma_f32_16x16x32_bf16 v[160:163], v[156:159], v[28:31], v[160:163]
	v_mfma_f32_16x16x32_bf16 v[164:167], v[156:159], v[60:63], v[164:167]
	s_waitcnt lgkmcnt(0)
	ds_read_b128 v[128:131], v233 offset:16896
	ds_read_b128 v[132:135], v233 offset:16960
	ds_read_b128 v[136:139], v233 offset:17024
	ds_read_b128 v[140:143], v233 offset:17088
	ds_read_b128 v[144:147], v233 offset:17152
	ds_read_b128 v[148:151], v233 offset:17216
	ds_read_b128 v[152:155], v233 offset:17280
	ds_read_b128 v[156:159], v233 offset:17344
	v_mfma_f32_16x16x32_bf16 v[168:171], v[184:187], v[0:3], 0
	v_fma_f32 v216, v160, v178, -v180
	v_fma_f32 v217, v161, v178, -v180
	v_mfma_f32_16x16x32_bf16 v[172:175], v[184:187], v[32:35], 0
	v_fma_f32 v218, v162, v178, -v180
	v_fma_f32 v219, v163, v178, -v180
	v_mfma_f32_16x16x32_bf16 v[168:171], v[188:191], v[4:7], v[168:171]
	v_exp_f32_e32 v216, v216
	v_exp_f32_e32 v217, v217
	v_mfma_f32_16x16x32_bf16 v[172:175], v[188:191], v[36:39], v[172:175]
	v_exp_f32_e32 v218, v218
	v_exp_f32_e32 v219, v219
	v_mfma_f32_16x16x32_bf16 v[168:171], v[192:195], v[8:11], v[168:171]
	v_fma_f32 v220, v164, v179, -v180
	v_fma_f32 v221, v165, v179, -v180
	v_mfma_f32_16x16x32_bf16 v[172:175], v[192:195], v[40:43], v[172:175]
	v_fma_f32 v222, v166, v179, -v180
	v_fma_f32 v223, v167, v179, -v180
	v_mfma_f32_16x16x32_bf16 v[168:171], v[196:199], v[12:15], v[168:171]
	v_exp_f32_e32 v220, v220
	v_exp_f32_e32 v221, v221
	v_mfma_f32_16x16x32_bf16 v[172:175], v[196:199], v[44:47], v[172:175]
	v_exp_f32_e32 v222, v222
	v_exp_f32_e32 v223, v223
	v_mfma_f32_16x16x32_bf16 v[168:171], v[200:203], v[16:19], v[168:171]
	v_add_f32_e32 v176, v176, v216
	v_add_f32_e32 v176, v176, v217
	v_mfma_f32_16x16x32_bf16 v[172:175], v[200:203], v[48:51], v[172:175]
	v_cvt_pk_bf16_f32 v64, v216, v217
	v_add_f32_e32 v176, v176, v218
	v_mfma_f32_16x16x32_bf16 v[168:171], v[204:207], v[20:23], v[168:171]
	v_add_f32_e32 v176, v176, v219
	v_cvt_pk_bf16_f32 v65, v218, v219
	v_mfma_f32_16x16x32_bf16 v[172:175], v[204:207], v[52:55], v[172:175]
	v_add_f32_e32 v177, v177, v220
	v_add_f32_e32 v177, v177, v221
	v_mfma_f32_16x16x32_bf16 v[168:171], v[208:211], v[24:27], v[168:171]
	v_cvt_pk_bf16_f32 v96, v220, v221
	v_add_f32_e32 v177, v177, v222
	v_mfma_f32_16x16x32_bf16 v[172:175], v[208:211], v[56:59], v[172:175]
	v_add_f32_e32 v177, v177, v223
	v_cvt_pk_bf16_f32 v97, v222, v223
	v_mfma_f32_16x16x32_bf16 v[168:171], v[212:215], v[28:31], v[168:171]
	v_mfma_f32_16x16x32_bf16 v[172:175], v[212:215], v[60:63], v[172:175]
	s_waitcnt lgkmcnt(0)
	ds_read_b128 v[184:187], v233 offset:25344
	ds_read_b128 v[188:191], v233 offset:25408
	ds_read_b128 v[192:195], v233 offset:25472
	ds_read_b128 v[196:199], v233 offset:25536
	ds_read_b128 v[200:203], v233 offset:25600
	ds_read_b128 v[204:207], v233 offset:25664
	ds_read_b128 v[208:211], v233 offset:25728
	ds_read_b128 v[212:215], v233 offset:25792
	v_mfma_f32_16x16x32_bf16 v[160:163], v[128:131], v[0:3], 0
	v_fma_f32 v216, v168, v178, -v180
	v_fma_f32 v217, v169, v178, -v180
	v_mfma_f32_16x16x32_bf16 v[164:167], v[128:131], v[32:35], 0
	v_fma_f32 v218, v170, v178, -v180
	v_fma_f32 v219, v171, v178, -v180
	v_mfma_f32_16x16x32_bf16 v[160:163], v[132:135], v[4:7], v[160:163]
	v_exp_f32_e32 v216, v216
	v_exp_f32_e32 v217, v217
	v_mfma_f32_16x16x32_bf16 v[164:167], v[132:135], v[36:39], v[164:167]
	v_exp_f32_e32 v218, v218
	v_exp_f32_e32 v219, v219
	v_mfma_f32_16x16x32_bf16 v[160:163], v[136:139], v[8:11], v[160:163]
	v_fma_f32 v220, v172, v179, -v180
	v_fma_f32 v221, v173, v179, -v180
	v_mfma_f32_16x16x32_bf16 v[164:167], v[136:139], v[40:43], v[164:167]
	v_fma_f32 v222, v174, v179, -v180
	v_fma_f32 v223, v175, v179, -v180
	v_mfma_f32_16x16x32_bf16 v[160:163], v[140:143], v[12:15], v[160:163]
	v_exp_f32_e32 v220, v220
	v_exp_f32_e32 v221, v221
	v_mfma_f32_16x16x32_bf16 v[164:167], v[140:143], v[44:47], v[164:167]
	v_exp_f32_e32 v222, v222
	v_exp_f32_e32 v223, v223
	v_mfma_f32_16x16x32_bf16 v[160:163], v[144:147], v[16:19], v[160:163]
	v_add_f32_e32 v176, v176, v216
	v_add_f32_e32 v176, v176, v217
	v_mfma_f32_16x16x32_bf16 v[164:167], v[144:147], v[48:51], v[164:167]
	v_cvt_pk_bf16_f32 v66, v216, v217
	v_add_f32_e32 v176, v176, v218
	v_mfma_f32_16x16x32_bf16 v[160:163], v[148:151], v[20:23], v[160:163]
	v_add_f32_e32 v176, v176, v219
	v_cvt_pk_bf16_f32 v67, v218, v219
	v_mfma_f32_16x16x32_bf16 v[164:167], v[148:151], v[52:55], v[164:167]
	v_add_f32_e32 v177, v177, v220
	v_add_f32_e32 v177, v177, v221
	v_mfma_f32_16x16x32_bf16 v[160:163], v[152:155], v[24:27], v[160:163]
	v_cvt_pk_bf16_f32 v98, v220, v221
	v_add_f32_e32 v177, v177, v222
	v_mfma_f32_16x16x32_bf16 v[164:167], v[152:155], v[56:59], v[164:167]
	v_add_f32_e32 v177, v177, v223
	v_cvt_pk_bf16_f32 v99, v222, v223
	v_mfma_f32_16x16x32_bf16 v[160:163], v[156:159], v[28:31], v[160:163]
	v_mfma_f32_16x16x32_bf16 v[164:167], v[156:159], v[60:63], v[164:167]
	s_waitcnt lgkmcnt(0)
	ds_read_b128 v[128:131], v233 offset:33792
	ds_read_b128 v[132:135], v233 offset:33856
	ds_read_b128 v[136:139], v233 offset:33920
	ds_read_b128 v[140:143], v233 offset:33984
	ds_read_b128 v[144:147], v233 offset:34048
	ds_read_b128 v[148:151], v233 offset:34112
	ds_read_b128 v[152:155], v233 offset:34176
	ds_read_b128 v[156:159], v233 offset:34240
	v_mfma_f32_16x16x32_bf16 v[168:171], v[184:187], v[0:3], 0
	v_fma_f32 v216, v160, v178, -v180
	v_fma_f32 v217, v161, v178, -v180
	v_mfma_f32_16x16x32_bf16 v[172:175], v[184:187], v[32:35], 0
	v_fma_f32 v218, v162, v178, -v180
	v_fma_f32 v219, v163, v178, -v180
	v_mfma_f32_16x16x32_bf16 v[168:171], v[188:191], v[4:7], v[168:171]
	v_exp_f32_e32 v216, v216
	v_exp_f32_e32 v217, v217
	v_mfma_f32_16x16x32_bf16 v[172:175], v[188:191], v[36:39], v[172:175]
	v_exp_f32_e32 v218, v218
	v_exp_f32_e32 v219, v219
	v_mfma_f32_16x16x32_bf16 v[168:171], v[192:195], v[8:11], v[168:171]
	v_fma_f32 v220, v164, v179, -v180
	v_fma_f32 v221, v165, v179, -v180
	v_mfma_f32_16x16x32_bf16 v[172:175], v[192:195], v[40:43], v[172:175]
	v_fma_f32 v222, v166, v179, -v180
	v_fma_f32 v223, v167, v179, -v180
	v_mfma_f32_16x16x32_bf16 v[168:171], v[196:199], v[12:15], v[168:171]
	v_exp_f32_e32 v220, v220
	v_exp_f32_e32 v221, v221
	v_mfma_f32_16x16x32_bf16 v[172:175], v[196:199], v[44:47], v[172:175]
	v_exp_f32_e32 v222, v222
	v_exp_f32_e32 v223, v223
	v_mfma_f32_16x16x32_bf16 v[168:171], v[200:203], v[16:19], v[168:171]
	v_add_f32_e32 v176, v176, v216
	v_add_f32_e32 v176, v176, v217
	v_mfma_f32_16x16x32_bf16 v[172:175], v[200:203], v[48:51], v[172:175]
	v_cvt_pk_bf16_f32 v68, v216, v217
	v_add_f32_e32 v176, v176, v218
	v_mfma_f32_16x16x32_bf16 v[168:171], v[204:207], v[20:23], v[168:171]
	v_add_f32_e32 v176, v176, v219
	v_cvt_pk_bf16_f32 v69, v218, v219
	v_mfma_f32_16x16x32_bf16 v[172:175], v[204:207], v[52:55], v[172:175]
	v_add_f32_e32 v177, v177, v220
	v_add_f32_e32 v177, v177, v221
	v_mfma_f32_16x16x32_bf16 v[168:171], v[208:211], v[24:27], v[168:171]
	v_cvt_pk_bf16_f32 v100, v220, v221
	v_add_f32_e32 v177, v177, v222
	v_mfma_f32_16x16x32_bf16 v[172:175], v[208:211], v[56:59], v[172:175]
	v_add_f32_e32 v177, v177, v223
	v_cvt_pk_bf16_f32 v101, v222, v223
	v_mfma_f32_16x16x32_bf16 v[168:171], v[212:215], v[28:31], v[168:171]
	v_mfma_f32_16x16x32_bf16 v[172:175], v[212:215], v[60:63], v[172:175]
	s_waitcnt lgkmcnt(0)
	ds_read_b128 v[184:187], v233 offset:42240
	ds_read_b128 v[188:191], v233 offset:42304
	ds_read_b128 v[192:195], v233 offset:42368
	ds_read_b128 v[196:199], v233 offset:42432
	ds_read_b128 v[200:203], v233 offset:42496
	ds_read_b128 v[204:207], v233 offset:42560
	ds_read_b128 v[208:211], v233 offset:42624
	ds_read_b128 v[212:215], v233 offset:42688
	v_mfma_f32_16x16x32_bf16 v[160:163], v[128:131], v[0:3], 0
	v_fma_f32 v216, v168, v178, -v180
	v_fma_f32 v217, v169, v178, -v180
	v_mfma_f32_16x16x32_bf16 v[164:167], v[128:131], v[32:35], 0
	v_fma_f32 v218, v170, v178, -v180
	v_fma_f32 v219, v171, v178, -v180
	v_mfma_f32_16x16x32_bf16 v[160:163], v[132:135], v[4:7], v[160:163]
	v_exp_f32_e32 v216, v216
	v_exp_f32_e32 v217, v217
	v_mfma_f32_16x16x32_bf16 v[164:167], v[132:135], v[36:39], v[164:167]
	v_exp_f32_e32 v218, v218
	v_exp_f32_e32 v219, v219
	v_mfma_f32_16x16x32_bf16 v[160:163], v[136:139], v[8:11], v[160:163]
	v_fma_f32 v220, v172, v179, -v180
	v_fma_f32 v221, v173, v179, -v180
	v_mfma_f32_16x16x32_bf16 v[164:167], v[136:139], v[40:43], v[164:167]
	v_fma_f32 v222, v174, v179, -v180
	v_fma_f32 v223, v175, v179, -v180
	v_mfma_f32_16x16x32_bf16 v[160:163], v[140:143], v[12:15], v[160:163]
	v_exp_f32_e32 v220, v220
	v_exp_f32_e32 v221, v221
	v_mfma_f32_16x16x32_bf16 v[164:167], v[140:143], v[44:47], v[164:167]
	v_exp_f32_e32 v222, v222
	v_exp_f32_e32 v223, v223
	v_mfma_f32_16x16x32_bf16 v[160:163], v[144:147], v[16:19], v[160:163]
	v_add_f32_e32 v176, v176, v216
	v_add_f32_e32 v176, v176, v217
	v_mfma_f32_16x16x32_bf16 v[164:167], v[144:147], v[48:51], v[164:167]
	v_cvt_pk_bf16_f32 v70, v216, v217
	v_add_f32_e32 v176, v176, v218
	v_mfma_f32_16x16x32_bf16 v[160:163], v[148:151], v[20:23], v[160:163]
	v_add_f32_e32 v176, v176, v219
	v_cvt_pk_bf16_f32 v71, v218, v219
	v_mfma_f32_16x16x32_bf16 v[164:167], v[148:151], v[52:55], v[164:167]
	v_add_f32_e32 v177, v177, v220
	v_add_f32_e32 v177, v177, v221
	v_mfma_f32_16x16x32_bf16 v[160:163], v[152:155], v[24:27], v[160:163]
	v_cvt_pk_bf16_f32 v102, v220, v221
	v_add_f32_e32 v177, v177, v222
	v_mfma_f32_16x16x32_bf16 v[164:167], v[152:155], v[56:59], v[164:167]
	v_add_f32_e32 v177, v177, v223
	v_cvt_pk_bf16_f32 v103, v222, v223
	v_mfma_f32_16x16x32_bf16 v[160:163], v[156:159], v[28:31], v[160:163]
	v_mfma_f32_16x16x32_bf16 v[164:167], v[156:159], v[60:63], v[164:167]
	s_waitcnt lgkmcnt(0)
	ds_read_b128 v[128:131], v233 offset:50688
	ds_read_b128 v[132:135], v233 offset:50752
	ds_read_b128 v[136:139], v233 offset:50816
	ds_read_b128 v[140:143], v233 offset:50880
	ds_read_b128 v[144:147], v233 offset:50944
	ds_read_b128 v[148:151], v233 offset:51008
	ds_read_b128 v[152:155], v233 offset:51072
	ds_read_b128 v[156:159], v233 offset:51136
	v_mfma_f32_16x16x32_bf16 v[168:171], v[184:187], v[0:3], 0
	v_fma_f32 v216, v160, v178, -v180
	v_fma_f32 v217, v161, v178, -v180
	v_mfma_f32_16x16x32_bf16 v[172:175], v[184:187], v[32:35], 0
	v_fma_f32 v218, v162, v178, -v180
	v_fma_f32 v219, v163, v178, -v180
	v_mfma_f32_16x16x32_bf16 v[168:171], v[188:191], v[4:7], v[168:171]
	v_exp_f32_e32 v216, v216
	v_exp_f32_e32 v217, v217
	v_mfma_f32_16x16x32_bf16 v[172:175], v[188:191], v[36:39], v[172:175]
	v_exp_f32_e32 v218, v218
	v_exp_f32_e32 v219, v219
	v_mfma_f32_16x16x32_bf16 v[168:171], v[192:195], v[8:11], v[168:171]
	v_fma_f32 v220, v164, v179, -v180
	v_fma_f32 v221, v165, v179, -v180
	v_mfma_f32_16x16x32_bf16 v[172:175], v[192:195], v[40:43], v[172:175]
	v_fma_f32 v222, v166, v179, -v180
	v_fma_f32 v223, v167, v179, -v180
	v_mfma_f32_16x16x32_bf16 v[168:171], v[196:199], v[12:15], v[168:171]
	v_exp_f32_e32 v220, v220
	v_exp_f32_e32 v221, v221
	v_mfma_f32_16x16x32_bf16 v[172:175], v[196:199], v[44:47], v[172:175]
	v_exp_f32_e32 v222, v222
	v_exp_f32_e32 v223, v223
	v_mfma_f32_16x16x32_bf16 v[168:171], v[200:203], v[16:19], v[168:171]
	v_add_f32_e32 v176, v176, v216
	v_add_f32_e32 v176, v176, v217
	v_mfma_f32_16x16x32_bf16 v[172:175], v[200:203], v[48:51], v[172:175]
	v_cvt_pk_bf16_f32 v72, v216, v217
	v_add_f32_e32 v176, v176, v218
	v_mfma_f32_16x16x32_bf16 v[168:171], v[204:207], v[20:23], v[168:171]
	v_add_f32_e32 v176, v176, v219
	v_cvt_pk_bf16_f32 v73, v218, v219
	v_mfma_f32_16x16x32_bf16 v[172:175], v[204:207], v[52:55], v[172:175]
	v_add_f32_e32 v177, v177, v220
	v_add_f32_e32 v177, v177, v221
	v_mfma_f32_16x16x32_bf16 v[168:171], v[208:211], v[24:27], v[168:171]
	v_cvt_pk_bf16_f32 v104, v220, v221
	v_add_f32_e32 v177, v177, v222
	v_mfma_f32_16x16x32_bf16 v[172:175], v[208:211], v[56:59], v[172:175]
	v_add_f32_e32 v177, v177, v223
	v_cvt_pk_bf16_f32 v105, v222, v223
	v_mfma_f32_16x16x32_bf16 v[168:171], v[212:215], v[28:31], v[168:171]
	v_mfma_f32_16x16x32_bf16 v[172:175], v[212:215], v[60:63], v[172:175]
	s_waitcnt lgkmcnt(0)
	v_add_u32_e32 v233, 59136, v233
	ds_read_b128 v[184:187], v233 offset:0
	ds_read_b128 v[188:191], v233 offset:64
	ds_read_b128 v[192:195], v233 offset:128
	ds_read_b128 v[196:199], v233 offset:192
	ds_read_b128 v[200:203], v233 offset:256
	ds_read_b128 v[204:207], v233 offset:320
	ds_read_b128 v[208:211], v233 offset:384
	ds_read_b128 v[212:215], v233 offset:448
	v_mfma_f32_16x16x32_bf16 v[160:163], v[128:131], v[0:3], 0
	v_fma_f32 v216, v168, v178, -v180
	v_fma_f32 v217, v169, v178, -v180
	v_mfma_f32_16x16x32_bf16 v[164:167], v[128:131], v[32:35], 0
	v_fma_f32 v218, v170, v178, -v180
	v_fma_f32 v219, v171, v178, -v180
	v_mfma_f32_16x16x32_bf16 v[160:163], v[132:135], v[4:7], v[160:163]
	v_exp_f32_e32 v216, v216
	v_exp_f32_e32 v217, v217
	v_mfma_f32_16x16x32_bf16 v[164:167], v[132:135], v[36:39], v[164:167]
	v_exp_f32_e32 v218, v218
	v_exp_f32_e32 v219, v219
	v_mfma_f32_16x16x32_bf16 v[160:163], v[136:139], v[8:11], v[160:163]
	v_fma_f32 v220, v172, v179, -v180
	v_fma_f32 v221, v173, v179, -v180
	v_mfma_f32_16x16x32_bf16 v[164:167], v[136:139], v[40:43], v[164:167]
	v_fma_f32 v222, v174, v179, -v180
	v_fma_f32 v223, v175, v179, -v180
	v_mfma_f32_16x16x32_bf16 v[160:163], v[140:143], v[12:15], v[160:163]
	v_exp_f32_e32 v220, v220
	v_exp_f32_e32 v221, v221
	v_mfma_f32_16x16x32_bf16 v[164:167], v[140:143], v[44:47], v[164:167]
	v_exp_f32_e32 v222, v222
	v_exp_f32_e32 v223, v223
	v_mfma_f32_16x16x32_bf16 v[160:163], v[144:147], v[16:19], v[160:163]
	v_add_f32_e32 v176, v176, v216
	v_add_f32_e32 v176, v176, v217
	v_mfma_f32_16x16x32_bf16 v[164:167], v[144:147], v[48:51], v[164:167]
	v_cvt_pk_bf16_f32 v74, v216, v217
	v_add_f32_e32 v176, v176, v218
	v_mfma_f32_16x16x32_bf16 v[160:163], v[148:151], v[20:23], v[160:163]
	v_add_f32_e32 v176, v176, v219
	v_cvt_pk_bf16_f32 v75, v218, v219
	v_mfma_f32_16x16x32_bf16 v[164:167], v[148:151], v[52:55], v[164:167]
	v_add_f32_e32 v177, v177, v220
	v_add_f32_e32 v177, v177, v221
	v_mfma_f32_16x16x32_bf16 v[160:163], v[152:155], v[24:27], v[160:163]
	v_cvt_pk_bf16_f32 v106, v220, v221
	v_add_f32_e32 v177, v177, v222
	v_mfma_f32_16x16x32_bf16 v[164:167], v[152:155], v[56:59], v[164:167]
	v_add_f32_e32 v177, v177, v223
	v_cvt_pk_bf16_f32 v107, v222, v223
	v_mfma_f32_16x16x32_bf16 v[160:163], v[156:159], v[28:31], v[160:163]
	v_mfma_f32_16x16x32_bf16 v[164:167], v[156:159], v[60:63], v[164:167]
	s_waitcnt lgkmcnt(0)
	ds_read_b128 v[128:131], v233 offset:8448
	ds_read_b128 v[132:135], v233 offset:8512
	ds_read_b128 v[136:139], v233 offset:8576
	ds_read_b128 v[140:143], v233 offset:8640
	ds_read_b128 v[144:147], v233 offset:8704
	ds_read_b128 v[148:151], v233 offset:8768
	ds_read_b128 v[152:155], v233 offset:8832
	ds_read_b128 v[156:159], v233 offset:8896
	v_mfma_f32_16x16x32_bf16 v[168:171], v[184:187], v[0:3], 0
	v_fma_f32 v216, v160, v178, -v180
	v_fma_f32 v217, v161, v178, -v180
	v_mfma_f32_16x16x32_bf16 v[172:175], v[184:187], v[32:35], 0
	v_fma_f32 v218, v162, v178, -v180
	v_fma_f32 v219, v163, v178, -v180
	v_mfma_f32_16x16x32_bf16 v[168:171], v[188:191], v[4:7], v[168:171]
	v_exp_f32_e32 v216, v216
	v_exp_f32_e32 v217, v217
	v_mfma_f32_16x16x32_bf16 v[172:175], v[188:191], v[36:39], v[172:175]
	v_exp_f32_e32 v218, v218
	v_exp_f32_e32 v219, v219
	v_mfma_f32_16x16x32_bf16 v[168:171], v[192:195], v[8:11], v[168:171]
	v_fma_f32 v220, v164, v179, -v180
	v_fma_f32 v221, v165, v179, -v180
	v_mfma_f32_16x16x32_bf16 v[172:175], v[192:195], v[40:43], v[172:175]
	v_fma_f32 v222, v166, v179, -v180
	v_fma_f32 v223, v167, v179, -v180
	v_mfma_f32_16x16x32_bf16 v[168:171], v[196:199], v[12:15], v[168:171]
	v_exp_f32_e32 v220, v220
	v_exp_f32_e32 v221, v221
	v_mfma_f32_16x16x32_bf16 v[172:175], v[196:199], v[44:47], v[172:175]
	v_exp_f32_e32 v222, v222
	v_exp_f32_e32 v223, v223
	v_mfma_f32_16x16x32_bf16 v[168:171], v[200:203], v[16:19], v[168:171]
	v_add_f32_e32 v176, v176, v216
	v_add_f32_e32 v176, v176, v217
	v_mfma_f32_16x16x32_bf16 v[172:175], v[200:203], v[48:51], v[172:175]
	v_cvt_pk_bf16_f32 v76, v216, v217
	v_add_f32_e32 v176, v176, v218
	v_mfma_f32_16x16x32_bf16 v[168:171], v[204:207], v[20:23], v[168:171]
	v_add_f32_e32 v176, v176, v219
	v_cvt_pk_bf16_f32 v77, v218, v219
	v_mfma_f32_16x16x32_bf16 v[172:175], v[204:207], v[52:55], v[172:175]
	v_add_f32_e32 v177, v177, v220
	v_add_f32_e32 v177, v177, v221
	v_mfma_f32_16x16x32_bf16 v[168:171], v[208:211], v[24:27], v[168:171]
	v_cvt_pk_bf16_f32 v108, v220, v221
	v_add_f32_e32 v177, v177, v222
	v_mfma_f32_16x16x32_bf16 v[172:175], v[208:211], v[56:59], v[172:175]
	v_add_f32_e32 v177, v177, v223
	v_cvt_pk_bf16_f32 v109, v222, v223
	v_mfma_f32_16x16x32_bf16 v[168:171], v[212:215], v[28:31], v[168:171]
	v_mfma_f32_16x16x32_bf16 v[172:175], v[212:215], v[60:63], v[172:175]
	s_waitcnt lgkmcnt(0)
	ds_read_b128 v[184:187], v233 offset:16896
	ds_read_b128 v[188:191], v233 offset:16960
	ds_read_b128 v[192:195], v233 offset:17024
	ds_read_b128 v[196:199], v233 offset:17088
	ds_read_b128 v[200:203], v233 offset:17152
	ds_read_b128 v[204:207], v233 offset:17216
	ds_read_b128 v[208:211], v233 offset:17280
	ds_read_b128 v[212:215], v233 offset:17344
	v_mfma_f32_16x16x32_bf16 v[160:163], v[128:131], v[0:3], 0
	v_fma_f32 v216, v168, v178, -v180
	v_fma_f32 v217, v169, v178, -v180
	v_mfma_f32_16x16x32_bf16 v[164:167], v[128:131], v[32:35], 0
	v_fma_f32 v218, v170, v178, -v180
	v_fma_f32 v219, v171, v178, -v180
	v_mfma_f32_16x16x32_bf16 v[160:163], v[132:135], v[4:7], v[160:163]
	v_exp_f32_e32 v216, v216
	v_exp_f32_e32 v217, v217
	v_mfma_f32_16x16x32_bf16 v[164:167], v[132:135], v[36:39], v[164:167]
	v_exp_f32_e32 v218, v218
	v_exp_f32_e32 v219, v219
	v_mfma_f32_16x16x32_bf16 v[160:163], v[136:139], v[8:11], v[160:163]
	v_fma_f32 v220, v172, v179, -v180
	v_fma_f32 v221, v173, v179, -v180
	v_mfma_f32_16x16x32_bf16 v[164:167], v[136:139], v[40:43], v[164:167]
	v_fma_f32 v222, v174, v179, -v180
	v_fma_f32 v223, v175, v179, -v180
	v_mfma_f32_16x16x32_bf16 v[160:163], v[140:143], v[12:15], v[160:163]
	v_exp_f32_e32 v220, v220
	v_exp_f32_e32 v221, v221
	v_mfma_f32_16x16x32_bf16 v[164:167], v[140:143], v[44:47], v[164:167]
	v_exp_f32_e32 v222, v222
	v_exp_f32_e32 v223, v223
	v_mfma_f32_16x16x32_bf16 v[160:163], v[144:147], v[16:19], v[160:163]
	v_add_f32_e32 v176, v176, v216
	v_add_f32_e32 v176, v176, v217
	v_mfma_f32_16x16x32_bf16 v[164:167], v[144:147], v[48:51], v[164:167]
	v_cvt_pk_bf16_f32 v78, v216, v217
	v_add_f32_e32 v176, v176, v218
	v_mfma_f32_16x16x32_bf16 v[160:163], v[148:151], v[20:23], v[160:163]
	v_add_f32_e32 v176, v176, v219
	v_cvt_pk_bf16_f32 v79, v218, v219
	v_mfma_f32_16x16x32_bf16 v[164:167], v[148:151], v[52:55], v[164:167]
	v_add_f32_e32 v177, v177, v220
	v_add_f32_e32 v177, v177, v221
	v_mfma_f32_16x16x32_bf16 v[160:163], v[152:155], v[24:27], v[160:163]
	v_cvt_pk_bf16_f32 v110, v220, v221
	v_add_f32_e32 v177, v177, v222
	v_mfma_f32_16x16x32_bf16 v[164:167], v[152:155], v[56:59], v[164:167]
	v_add_f32_e32 v177, v177, v223
	v_cvt_pk_bf16_f32 v111, v222, v223
	v_mfma_f32_16x16x32_bf16 v[160:163], v[156:159], v[28:31], v[160:163]
	v_mfma_f32_16x16x32_bf16 v[164:167], v[156:159], v[60:63], v[164:167]
	s_waitcnt lgkmcnt(0)
	ds_read_b128 v[128:131], v233 offset:25344
	ds_read_b128 v[132:135], v233 offset:25408
	ds_read_b128 v[136:139], v233 offset:25472
	ds_read_b128 v[140:143], v233 offset:25536
	ds_read_b128 v[144:147], v233 offset:25600
	ds_read_b128 v[148:151], v233 offset:25664
	ds_read_b128 v[152:155], v233 offset:25728
	ds_read_b128 v[156:159], v233 offset:25792
	v_mfma_f32_16x16x32_bf16 v[168:171], v[184:187], v[0:3], 0
	v_fma_f32 v216, v160, v178, -v180
	v_fma_f32 v217, v161, v178, -v180
	v_mfma_f32_16x16x32_bf16 v[172:175], v[184:187], v[32:35], 0
	v_fma_f32 v218, v162, v178, -v180
	v_fma_f32 v219, v163, v178, -v180
	v_mfma_f32_16x16x32_bf16 v[168:171], v[188:191], v[4:7], v[168:171]
	v_exp_f32_e32 v216, v216
	v_exp_f32_e32 v217, v217
	v_mfma_f32_16x16x32_bf16 v[172:175], v[188:191], v[36:39], v[172:175]
	v_exp_f32_e32 v218, v218
	v_exp_f32_e32 v219, v219
	v_mfma_f32_16x16x32_bf16 v[168:171], v[192:195], v[8:11], v[168:171]
	v_fma_f32 v220, v164, v179, -v180
	v_fma_f32 v221, v165, v179, -v180
	v_mfma_f32_16x16x32_bf16 v[172:175], v[192:195], v[40:43], v[172:175]
	v_fma_f32 v222, v166, v179, -v180
	v_fma_f32 v223, v167, v179, -v180
	v_mfma_f32_16x16x32_bf16 v[168:171], v[196:199], v[12:15], v[168:171]
	v_exp_f32_e32 v220, v220
	v_exp_f32_e32 v221, v221
	v_mfma_f32_16x16x32_bf16 v[172:175], v[196:199], v[44:47], v[172:175]
	v_exp_f32_e32 v222, v222
	v_exp_f32_e32 v223, v223
	v_mfma_f32_16x16x32_bf16 v[168:171], v[200:203], v[16:19], v[168:171]
	v_add_f32_e32 v176, v176, v216
	v_add_f32_e32 v176, v176, v217
	v_mfma_f32_16x16x32_bf16 v[172:175], v[200:203], v[48:51], v[172:175]
	v_cvt_pk_bf16_f32 v80, v216, v217
	v_add_f32_e32 v176, v176, v218
	v_mfma_f32_16x16x32_bf16 v[168:171], v[204:207], v[20:23], v[168:171]
	v_add_f32_e32 v176, v176, v219
	v_cvt_pk_bf16_f32 v81, v218, v219
	v_mfma_f32_16x16x32_bf16 v[172:175], v[204:207], v[52:55], v[172:175]
	v_add_f32_e32 v177, v177, v220
	v_add_f32_e32 v177, v177, v221
	v_mfma_f32_16x16x32_bf16 v[168:171], v[208:211], v[24:27], v[168:171]
	v_cvt_pk_bf16_f32 v112, v220, v221
	v_add_f32_e32 v177, v177, v222
	v_mfma_f32_16x16x32_bf16 v[172:175], v[208:211], v[56:59], v[172:175]
	v_add_f32_e32 v177, v177, v223
	v_cvt_pk_bf16_f32 v113, v222, v223
	v_mfma_f32_16x16x32_bf16 v[168:171], v[212:215], v[28:31], v[168:171]
	v_mfma_f32_16x16x32_bf16 v[172:175], v[212:215], v[60:63], v[172:175]
	s_waitcnt lgkmcnt(0)
	ds_read_b128 v[184:187], v233 offset:33792
	ds_read_b128 v[188:191], v233 offset:33856
	ds_read_b128 v[192:195], v233 offset:33920
	ds_read_b128 v[196:199], v233 offset:33984
	ds_read_b128 v[200:203], v233 offset:34048
	ds_read_b128 v[204:207], v233 offset:34112
	ds_read_b128 v[208:211], v233 offset:34176
	ds_read_b128 v[212:215], v233 offset:34240
	v_mfma_f32_16x16x32_bf16 v[160:163], v[128:131], v[0:3], 0
	v_fma_f32 v216, v168, v178, -v180
	v_fma_f32 v217, v169, v178, -v180
	v_mfma_f32_16x16x32_bf16 v[164:167], v[128:131], v[32:35], 0
	v_fma_f32 v218, v170, v178, -v180
	v_fma_f32 v219, v171, v178, -v180
	v_mfma_f32_16x16x32_bf16 v[160:163], v[132:135], v[4:7], v[160:163]
	v_exp_f32_e32 v216, v216
	v_exp_f32_e32 v217, v217
	v_mfma_f32_16x16x32_bf16 v[164:167], v[132:135], v[36:39], v[164:167]
	v_exp_f32_e32 v218, v218
	v_exp_f32_e32 v219, v219
	v_mfma_f32_16x16x32_bf16 v[160:163], v[136:139], v[8:11], v[160:163]
	v_fma_f32 v220, v172, v179, -v180
	v_fma_f32 v221, v173, v179, -v180
	v_mfma_f32_16x16x32_bf16 v[164:167], v[136:139], v[40:43], v[164:167]
	v_fma_f32 v222, v174, v179, -v180
	v_fma_f32 v223, v175, v179, -v180
	v_mfma_f32_16x16x32_bf16 v[160:163], v[140:143], v[12:15], v[160:163]
	v_exp_f32_e32 v220, v220
	v_exp_f32_e32 v221, v221
	v_mfma_f32_16x16x32_bf16 v[164:167], v[140:143], v[44:47], v[164:167]
	v_exp_f32_e32 v222, v222
	v_exp_f32_e32 v223, v223
	v_mfma_f32_16x16x32_bf16 v[160:163], v[144:147], v[16:19], v[160:163]
	v_add_f32_e32 v176, v176, v216
	v_add_f32_e32 v176, v176, v217
	v_mfma_f32_16x16x32_bf16 v[164:167], v[144:147], v[48:51], v[164:167]
	v_cvt_pk_bf16_f32 v82, v216, v217
	v_add_f32_e32 v176, v176, v218
	v_mfma_f32_16x16x32_bf16 v[160:163], v[148:151], v[20:23], v[160:163]
	v_add_f32_e32 v176, v176, v219
	v_cvt_pk_bf16_f32 v83, v218, v219
	v_mfma_f32_16x16x32_bf16 v[164:167], v[148:151], v[52:55], v[164:167]
	v_add_f32_e32 v177, v177, v220
	v_add_f32_e32 v177, v177, v221
	v_mfma_f32_16x16x32_bf16 v[160:163], v[152:155], v[24:27], v[160:163]
	v_cvt_pk_bf16_f32 v114, v220, v221
	v_add_f32_e32 v177, v177, v222
	v_mfma_f32_16x16x32_bf16 v[164:167], v[152:155], v[56:59], v[164:167]
	v_add_f32_e32 v177, v177, v223
	v_cvt_pk_bf16_f32 v115, v222, v223
	v_mfma_f32_16x16x32_bf16 v[160:163], v[156:159], v[28:31], v[160:163]
	v_mfma_f32_16x16x32_bf16 v[164:167], v[156:159], v[60:63], v[164:167]
	s_waitcnt lgkmcnt(0)
	ds_read_b128 v[128:131], v233 offset:42240
	ds_read_b128 v[132:135], v233 offset:42304
	ds_read_b128 v[136:139], v233 offset:42368
	ds_read_b128 v[140:143], v233 offset:42432
	ds_read_b128 v[144:147], v233 offset:42496
	ds_read_b128 v[148:151], v233 offset:42560
	ds_read_b128 v[152:155], v233 offset:42624
	ds_read_b128 v[156:159], v233 offset:42688
	v_mfma_f32_16x16x32_bf16 v[168:171], v[184:187], v[0:3], 0
	v_fma_f32 v216, v160, v178, -v180
	v_fma_f32 v217, v161, v178, -v180
	v_mfma_f32_16x16x32_bf16 v[172:175], v[184:187], v[32:35], 0
	v_fma_f32 v218, v162, v178, -v180
	v_fma_f32 v219, v163, v178, -v180
	v_mfma_f32_16x16x32_bf16 v[168:171], v[188:191], v[4:7], v[168:171]
	v_exp_f32_e32 v216, v216
	v_exp_f32_e32 v217, v217
	v_mfma_f32_16x16x32_bf16 v[172:175], v[188:191], v[36:39], v[172:175]
	v_exp_f32_e32 v218, v218
	v_exp_f32_e32 v219, v219
	v_mfma_f32_16x16x32_bf16 v[168:171], v[192:195], v[8:11], v[168:171]
	v_fma_f32 v220, v164, v179, -v180
	v_fma_f32 v221, v165, v179, -v180
	v_mfma_f32_16x16x32_bf16 v[172:175], v[192:195], v[40:43], v[172:175]
	v_fma_f32 v222, v166, v179, -v180
	v_fma_f32 v223, v167, v179, -v180
	v_mfma_f32_16x16x32_bf16 v[168:171], v[196:199], v[12:15], v[168:171]
	v_exp_f32_e32 v220, v220
	v_exp_f32_e32 v221, v221
	v_mfma_f32_16x16x32_bf16 v[172:175], v[196:199], v[44:47], v[172:175]
	v_exp_f32_e32 v222, v222
	v_exp_f32_e32 v223, v223
	v_mfma_f32_16x16x32_bf16 v[168:171], v[200:203], v[16:19], v[168:171]
	v_add_f32_e32 v176, v176, v216
	v_add_f32_e32 v176, v176, v217
	v_mfma_f32_16x16x32_bf16 v[172:175], v[200:203], v[48:51], v[172:175]
	v_cvt_pk_bf16_f32 v84, v216, v217
	v_add_f32_e32 v176, v176, v218
	v_mfma_f32_16x16x32_bf16 v[168:171], v[204:207], v[20:23], v[168:171]
	v_add_f32_e32 v176, v176, v219
	v_cvt_pk_bf16_f32 v85, v218, v219
	v_mfma_f32_16x16x32_bf16 v[172:175], v[204:207], v[52:55], v[172:175]
	v_add_f32_e32 v177, v177, v220
	v_add_f32_e32 v177, v177, v221
	v_mfma_f32_16x16x32_bf16 v[168:171], v[208:211], v[24:27], v[168:171]
	v_cvt_pk_bf16_f32 v116, v220, v221
	v_add_f32_e32 v177, v177, v222
	v_mfma_f32_16x16x32_bf16 v[172:175], v[208:211], v[56:59], v[172:175]
	v_add_f32_e32 v177, v177, v223
	v_cvt_pk_bf16_f32 v117, v222, v223
	v_mfma_f32_16x16x32_bf16 v[168:171], v[212:215], v[28:31], v[168:171]
	v_mfma_f32_16x16x32_bf16 v[172:175], v[212:215], v[60:63], v[172:175]
	s_waitcnt lgkmcnt(0)
	ds_read_b128 v[184:187], v233 offset:50688
	ds_read_b128 v[188:191], v233 offset:50752
	ds_read_b128 v[192:195], v233 offset:50816
	ds_read_b128 v[196:199], v233 offset:50880
	ds_read_b128 v[200:203], v233 offset:50944
	ds_read_b128 v[204:207], v233 offset:51008
	ds_read_b128 v[208:211], v233 offset:51072
	ds_read_b128 v[212:215], v233 offset:51136
	v_mfma_f32_16x16x32_bf16 v[160:163], v[128:131], v[0:3], 0
	v_fma_f32 v216, v168, v178, -v180
	v_fma_f32 v217, v169, v178, -v180
	v_mfma_f32_16x16x32_bf16 v[164:167], v[128:131], v[32:35], 0
	v_fma_f32 v218, v170, v178, -v180
	v_fma_f32 v219, v171, v178, -v180
	v_mfma_f32_16x16x32_bf16 v[160:163], v[132:135], v[4:7], v[160:163]
	v_exp_f32_e32 v216, v216
	v_exp_f32_e32 v217, v217
	v_mfma_f32_16x16x32_bf16 v[164:167], v[132:135], v[36:39], v[164:167]
	v_exp_f32_e32 v218, v218
	v_exp_f32_e32 v219, v219
	v_mfma_f32_16x16x32_bf16 v[160:163], v[136:139], v[8:11], v[160:163]
	v_fma_f32 v220, v172, v179, -v180
	v_fma_f32 v221, v173, v179, -v180
	v_mfma_f32_16x16x32_bf16 v[164:167], v[136:139], v[40:43], v[164:167]
	v_fma_f32 v222, v174, v179, -v180
	v_fma_f32 v223, v175, v179, -v180
	v_mfma_f32_16x16x32_bf16 v[160:163], v[140:143], v[12:15], v[160:163]
	v_exp_f32_e32 v220, v220
	v_exp_f32_e32 v221, v221
	v_mfma_f32_16x16x32_bf16 v[164:167], v[140:143], v[44:47], v[164:167]
	v_exp_f32_e32 v222, v222
	v_exp_f32_e32 v223, v223
	v_mfma_f32_16x16x32_bf16 v[160:163], v[144:147], v[16:19], v[160:163]
	v_add_f32_e32 v176, v176, v216
	v_add_f32_e32 v176, v176, v217
	v_mfma_f32_16x16x32_bf16 v[164:167], v[144:147], v[48:51], v[164:167]
	v_cvt_pk_bf16_f32 v86, v216, v217
	v_add_f32_e32 v176, v176, v218
	v_mfma_f32_16x16x32_bf16 v[160:163], v[148:151], v[20:23], v[160:163]
	v_add_f32_e32 v176, v176, v219
	v_cvt_pk_bf16_f32 v87, v218, v219
	v_mfma_f32_16x16x32_bf16 v[164:167], v[148:151], v[52:55], v[164:167]
	v_add_f32_e32 v177, v177, v220
	v_add_f32_e32 v177, v177, v221
	v_mfma_f32_16x16x32_bf16 v[160:163], v[152:155], v[24:27], v[160:163]
	v_cvt_pk_bf16_f32 v118, v220, v221
	v_add_f32_e32 v177, v177, v222
	v_mfma_f32_16x16x32_bf16 v[164:167], v[152:155], v[56:59], v[164:167]
	v_add_f32_e32 v177, v177, v223
	v_cvt_pk_bf16_f32 v119, v222, v223
	v_mfma_f32_16x16x32_bf16 v[160:163], v[156:159], v[28:31], v[160:163]
	v_mfma_f32_16x16x32_bf16 v[164:167], v[156:159], v[60:63], v[164:167]
	s_waitcnt lgkmcnt(0)
	v_add_u32_e32 v233, 59136, v233
	ds_read_b128 v[128:131], v233 offset:0
	ds_read_b128 v[132:135], v233 offset:64
	ds_read_b128 v[136:139], v233 offset:128
	ds_read_b128 v[140:143], v233 offset:192
	ds_read_b128 v[144:147], v233 offset:256
	ds_read_b128 v[148:151], v233 offset:320
	ds_read_b128 v[152:155], v233 offset:384
	ds_read_b128 v[156:159], v233 offset:448
	v_mfma_f32_16x16x32_bf16 v[168:171], v[184:187], v[0:3], 0
	v_fma_f32 v216, v160, v178, -v180
	v_fma_f32 v217, v161, v178, -v180
	v_mfma_f32_16x16x32_bf16 v[172:175], v[184:187], v[32:35], 0
	v_fma_f32 v218, v162, v178, -v180
	v_fma_f32 v219, v163, v178, -v180
	v_mfma_f32_16x16x32_bf16 v[168:171], v[188:191], v[4:7], v[168:171]
	v_exp_f32_e32 v216, v216
	v_exp_f32_e32 v217, v217
	v_mfma_f32_16x16x32_bf16 v[172:175], v[188:191], v[36:39], v[172:175]
	v_exp_f32_e32 v218, v218
	v_exp_f32_e32 v219, v219
	v_mfma_f32_16x16x32_bf16 v[168:171], v[192:195], v[8:11], v[168:171]
	v_fma_f32 v220, v164, v179, -v180
	v_fma_f32 v221, v165, v179, -v180
	v_mfma_f32_16x16x32_bf16 v[172:175], v[192:195], v[40:43], v[172:175]
	v_fma_f32 v222, v166, v179, -v180
	v_fma_f32 v223, v167, v179, -v180
	v_mfma_f32_16x16x32_bf16 v[168:171], v[196:199], v[12:15], v[168:171]
	v_exp_f32_e32 v220, v220
	v_exp_f32_e32 v221, v221
	v_mfma_f32_16x16x32_bf16 v[172:175], v[196:199], v[44:47], v[172:175]
	v_exp_f32_e32 v222, v222
	v_exp_f32_e32 v223, v223
	v_mfma_f32_16x16x32_bf16 v[168:171], v[200:203], v[16:19], v[168:171]
	v_add_f32_e32 v176, v176, v216
	v_add_f32_e32 v176, v176, v217
	v_mfma_f32_16x16x32_bf16 v[172:175], v[200:203], v[48:51], v[172:175]
	v_cvt_pk_bf16_f32 v88, v216, v217
	v_add_f32_e32 v176, v176, v218
	v_mfma_f32_16x16x32_bf16 v[168:171], v[204:207], v[20:23], v[168:171]
	v_add_f32_e32 v176, v176, v219
	v_cvt_pk_bf16_f32 v89, v218, v219
	v_mfma_f32_16x16x32_bf16 v[172:175], v[204:207], v[52:55], v[172:175]
	v_add_f32_e32 v177, v177, v220
	v_add_f32_e32 v177, v177, v221
	v_mfma_f32_16x16x32_bf16 v[168:171], v[208:211], v[24:27], v[168:171]
	v_cvt_pk_bf16_f32 v120, v220, v221
	v_add_f32_e32 v177, v177, v222
	v_mfma_f32_16x16x32_bf16 v[172:175], v[208:211], v[56:59], v[172:175]
	v_add_f32_e32 v177, v177, v223
	v_cvt_pk_bf16_f32 v121, v222, v223
	v_mfma_f32_16x16x32_bf16 v[168:171], v[212:215], v[28:31], v[168:171]
	v_mfma_f32_16x16x32_bf16 v[172:175], v[212:215], v[60:63], v[172:175]
	s_waitcnt lgkmcnt(0)
	ds_read_b128 v[184:187], v233 offset:8448
	ds_read_b128 v[188:191], v233 offset:8512
	ds_read_b128 v[192:195], v233 offset:8576
	ds_read_b128 v[196:199], v233 offset:8640
	ds_read_b128 v[200:203], v233 offset:8704
	ds_read_b128 v[204:207], v233 offset:8768
	ds_read_b128 v[208:211], v233 offset:8832
	ds_read_b128 v[212:215], v233 offset:8896
	v_mfma_f32_16x16x32_bf16 v[160:163], v[128:131], v[0:3], 0
	v_fma_f32 v216, v168, v178, -v180
	v_fma_f32 v217, v169, v178, -v180
	v_mfma_f32_16x16x32_bf16 v[164:167], v[128:131], v[32:35], 0
	v_fma_f32 v218, v170, v178, -v180
	v_fma_f32 v219, v171, v178, -v180
	v_mfma_f32_16x16x32_bf16 v[160:163], v[132:135], v[4:7], v[160:163]
	v_exp_f32_e32 v216, v216
	v_exp_f32_e32 v217, v217
	v_mfma_f32_16x16x32_bf16 v[164:167], v[132:135], v[36:39], v[164:167]
	v_exp_f32_e32 v218, v218
	v_exp_f32_e32 v219, v219
	v_mfma_f32_16x16x32_bf16 v[160:163], v[136:139], v[8:11], v[160:163]
	v_fma_f32 v220, v172, v179, -v180
	v_fma_f32 v221, v173, v179, -v180
	v_mfma_f32_16x16x32_bf16 v[164:167], v[136:139], v[40:43], v[164:167]
	v_fma_f32 v222, v174, v179, -v180
	v_fma_f32 v223, v175, v179, -v180
	v_mfma_f32_16x16x32_bf16 v[160:163], v[140:143], v[12:15], v[160:163]
	v_exp_f32_e32 v220, v220
	v_exp_f32_e32 v221, v221
	v_mfma_f32_16x16x32_bf16 v[164:167], v[140:143], v[44:47], v[164:167]
	v_exp_f32_e32 v222, v222
	v_exp_f32_e32 v223, v223
	v_mfma_f32_16x16x32_bf16 v[160:163], v[144:147], v[16:19], v[160:163]
	v_add_f32_e32 v176, v176, v216
	v_add_f32_e32 v176, v176, v217
	v_mfma_f32_16x16x32_bf16 v[164:167], v[144:147], v[48:51], v[164:167]
	v_cvt_pk_bf16_f32 v90, v216, v217
	v_add_f32_e32 v176, v176, v218
	v_mfma_f32_16x16x32_bf16 v[160:163], v[148:151], v[20:23], v[160:163]
	v_add_f32_e32 v176, v176, v219
	v_cvt_pk_bf16_f32 v91, v218, v219
	v_mfma_f32_16x16x32_bf16 v[164:167], v[148:151], v[52:55], v[164:167]
	v_add_f32_e32 v177, v177, v220
	v_add_f32_e32 v177, v177, v221
	v_mfma_f32_16x16x32_bf16 v[160:163], v[152:155], v[24:27], v[160:163]
	v_cvt_pk_bf16_f32 v122, v220, v221
	v_add_f32_e32 v177, v177, v222
	v_mfma_f32_16x16x32_bf16 v[164:167], v[152:155], v[56:59], v[164:167]
	v_add_f32_e32 v177, v177, v223
	v_cvt_pk_bf16_f32 v123, v222, v223
	v_mfma_f32_16x16x32_bf16 v[160:163], v[156:159], v[28:31], v[160:163]
	v_mfma_f32_16x16x32_bf16 v[164:167], v[156:159], v[60:63], v[164:167]
	s_waitcnt lgkmcnt(0)
	s_nop 6
	v_mfma_f32_16x16x32_bf16 v[168:171], v[184:187], v[0:3], 0
	v_fma_f32 v216, v160, v178, -v180
	v_fma_f32 v217, v161, v178, -v180
	v_mfma_f32_16x16x32_bf16 v[172:175], v[184:187], v[32:35], 0
	v_fma_f32 v218, v162, v178, -v180
	v_fma_f32 v219, v163, v178, -v180
	v_mfma_f32_16x16x32_bf16 v[168:171], v[188:191], v[4:7], v[168:171]
	v_exp_f32_e32 v216, v216
	v_exp_f32_e32 v217, v217
	v_mfma_f32_16x16x32_bf16 v[172:175], v[188:191], v[36:39], v[172:175]
	v_exp_f32_e32 v218, v218
	v_exp_f32_e32 v219, v219
	v_mfma_f32_16x16x32_bf16 v[168:171], v[192:195], v[8:11], v[168:171]
	v_fma_f32 v220, v164, v179, -v180
	v_fma_f32 v221, v165, v179, -v180
	v_mfma_f32_16x16x32_bf16 v[172:175], v[192:195], v[40:43], v[172:175]
	v_fma_f32 v222, v166, v179, -v180
	v_fma_f32 v223, v167, v179, -v180
	v_mfma_f32_16x16x32_bf16 v[168:171], v[196:199], v[12:15], v[168:171]
	v_exp_f32_e32 v220, v220
	v_exp_f32_e32 v221, v221
	v_mfma_f32_16x16x32_bf16 v[172:175], v[196:199], v[44:47], v[172:175]
	v_exp_f32_e32 v222, v222
	v_exp_f32_e32 v223, v223
	v_mfma_f32_16x16x32_bf16 v[168:171], v[200:203], v[16:19], v[168:171]
	v_add_f32_e32 v176, v176, v216
	v_add_f32_e32 v176, v176, v217
	v_mfma_f32_16x16x32_bf16 v[172:175], v[200:203], v[48:51], v[172:175]
	v_cvt_pk_bf16_f32 v92, v216, v217
	v_add_f32_e32 v176, v176, v218
	v_mfma_f32_16x16x32_bf16 v[168:171], v[204:207], v[20:23], v[168:171]
	v_add_f32_e32 v176, v176, v219
	v_cvt_pk_bf16_f32 v93, v218, v219
	v_mfma_f32_16x16x32_bf16 v[172:175], v[204:207], v[52:55], v[172:175]
	v_add_f32_e32 v177, v177, v220
	v_add_f32_e32 v177, v177, v221
	v_mfma_f32_16x16x32_bf16 v[168:171], v[208:211], v[24:27], v[168:171]
	v_cvt_pk_bf16_f32 v124, v220, v221
	v_add_f32_e32 v177, v177, v222
	v_mfma_f32_16x16x32_bf16 v[172:175], v[208:211], v[56:59], v[172:175]
	v_add_f32_e32 v177, v177, v223
	v_cvt_pk_bf16_f32 v125, v222, v223
	v_mfma_f32_16x16x32_bf16 v[168:171], v[212:215], v[28:31], v[168:171]
	v_mfma_f32_16x16x32_bf16 v[172:175], v[212:215], v[60:63], v[172:175]
	s_nop 7
	v_fma_f32 v216, v168, v178, -v180
	v_fma_f32 v217, v169, v178, -v180
	v_fma_f32 v218, v170, v178, -v180
	v_fma_f32 v219, v171, v178, -v180
	v_exp_f32_e32 v216, v216
	v_exp_f32_e32 v217, v217
	v_exp_f32_e32 v218, v218
	v_exp_f32_e32 v219, v219
	v_fma_f32 v220, v172, v179, -v180
	v_fma_f32 v221, v173, v179, -v180
	v_fma_f32 v222, v174, v179, -v180
	v_fma_f32 v223, v175, v179, -v180
	v_exp_f32_e32 v220, v220
	v_exp_f32_e32 v221, v221
	v_exp_f32_e32 v222, v222
	v_exp_f32_e32 v223, v223
	v_add_f32_e32 v176, v176, v216
	v_add_f32_e32 v176, v176, v217
	v_cvt_pk_bf16_f32 v94, v216, v217
	v_add_f32_e32 v176, v176, v218
	v_add_f32_e32 v176, v176, v219
	v_cvt_pk_bf16_f32 v95, v218, v219
	v_add_f32_e32 v177, v177, v220
	v_add_f32_e32 v177, v177, v221
	v_cvt_pk_bf16_f32 v126, v220, v221
	v_add_f32_e32 v177, v177, v222
	v_add_f32_e32 v177, v177, v223
	v_cvt_pk_bf16_f32 v127, v222, v223
	s_barrier
	global_load_dwordx4 v[128:131], v225, s[8:9]
	s_add_u32 s8, s8, 0x14000
	s_addc_u32 s9, s9, 0
	global_load_dwordx4 v[132:135], v225, s[8:9]
	s_add_u32 s8, s8, 0x14000
	s_addc_u32 s9, s9, 0
	global_load_dwordx4 v[136:139], v225, s[8:9]
	s_add_u32 s8, s8, 0x14000
	s_addc_u32 s9, s9, 0
	global_load_dwordx4 v[140:143], v225, s[8:9]
	s_add_u32 s8, s8, 0x14000
	s_addc_u32 s9, s9, 0
	global_load_dwordx4 v[144:147], v225, s[8:9]
	s_add_u32 s8, s8, 0x14000
	s_addc_u32 s9, s9, 0
	global_load_dwordx4 v[148:151], v225, s[8:9]
	s_add_u32 s8, s8, 0x14000
	s_addc_u32 s9, s9, 0
	global_load_dwordx4 v[152:155], v225, s[8:9]
	s_add_u32 s8, s8, 0x14000
	s_addc_u32 s9, s9, 0
	global_load_dwordx4 v[156:159], v225, s[8:9]
	s_add_u32 s8, s8, 0x14000
	s_addc_u32 s9, s9, 0
	global_load_dwordx4 v[184:187], v225, s[8:9]
	s_add_u32 s8, s8, 0x14000
	s_addc_u32 s9, s9, 0
	global_load_dwordx4 v[188:191], v225, s[8:9]
	s_add_u32 s8, s8, 0x14000
	s_addc_u32 s9, s9, 0
	global_load_dwordx4 v[192:195], v225, s[8:9]
	s_add_u32 s8, s8, 0x14000
	s_addc_u32 s9, s9, 0
	global_load_dwordx4 v[196:199], v225, s[8:9]
	s_add_u32 s8, s8, 0x14000
	s_addc_u32 s9, s9, 0
	global_load_dwordx4 v[200:203], v225, s[8:9]
	s_add_u32 s8, s8, 0x14000
	s_addc_u32 s9, s9, 0
	global_load_dwordx4 v[204:207], v225, s[8:9]
	s_add_u32 s8, s8, 0x14000
	s_addc_u32 s9, s9, 0
	global_load_dwordx4 v[208:211], v225, s[8:9]
	s_add_u32 s8, s8, 0x14000
	s_addc_u32 s9, s9, 0
	global_load_dwordx4 v[212:215], v225, s[8:9]
	s_add_i32 s16, s69, s86
	s_cmpk_lt_i32 s16, 0x300
	s_cselect_b32 s16, s16, s69
	s_and_b32 s0, s16, 31
	s_lshr_b32 s1, s16, 8
	s_lshl_b32 s1, s1, 5
	s_add_i32 s1, s1, s0
	s_mul_i32 s0, s1, 2731
	s_lshr_b32 s0, s0, 16
	s_mul_i32 s17, s0, 24
	s_sub_i32 s1, s1, s17
	s_bfe_u32 s17, s16, 0x30005
	s_mul_i32 s17, s17, 24
	s_add_i32 s1, s1, s17
	s_lshl_b32 s11, s1, 19
	s_lshl_b32 s12, s0, 9
	s_add_u32 s11, s11, s12
	s_add_u32 s12, s11, 0xf000000
	s_add_u32 s10, s4, s12
	s_addc_u32 s11, s5, 0
	s_lshl_b32 s12, s1, 12
	s_lshl_b32 s13, s0, 2
	s_add_u32 s12, s12, s13
	s_add_u32 s12, s12, 0x1fa60000
	s_add_u32 s12, s4, s12
	s_addc_u32 s13, s5, 0
	global_load_dwordx4 v[0:3], v228, s[10:11] offset:0
	global_load_dwordx4 v[4:7], v228, s[10:11] offset:64
	global_load_dwordx4 v[8:11], v228, s[10:11] offset:128
	global_load_dwordx4 v[12:15], v228, s[10:11] offset:192
	global_load_dwordx4 v[16:19], v228, s[10:11] offset:256
	global_load_dwordx4 v[20:23], v228, s[10:11] offset:320
	global_load_dwordx4 v[24:27], v228, s[10:11] offset:384
	global_load_dwordx4 v[28:31], v228, s[10:11] offset:448
	global_load_dwordx4 v[32:35], v229, s[10:11] offset:0
	global_load_dwordx4 v[36:39], v229, s[10:11] offset:64
	global_load_dwordx4 v[40:43], v229, s[10:11] offset:128
	global_load_dwordx4 v[44:47], v229, s[10:11] offset:192
	global_load_dwordx4 v[48:51], v229, s[10:11] offset:256
	global_load_dwordx4 v[52:55], v229, s[10:11] offset:320
	global_load_dwordx4 v[56:59], v229, s[10:11] offset:384
	global_load_dwordx4 v[60:63], v229, s[10:11] offset:448
	global_load_dword v247, v230, s[12:13]
	global_load_dword v248, v230, s[12:13] offset:2048
	ds_bpermute_b32 v242, v236, v176
	s_waitcnt lgkmcnt(0)
	v_add_f32_e32 v176, v176, v242
	ds_bpermute_b32 v242, v237, v176
	s_waitcnt lgkmcnt(0)
	v_add_f32_e32 v176, v176, v242
	ds_bpermute_b32 v242, v236, v177
	s_waitcnt lgkmcnt(0)
	v_add_f32_e32 v177, v177, v242
	ds_bpermute_b32 v242, v237, v177
	s_waitcnt lgkmcnt(0)
	v_add_f32_e32 v177, v177, v242
	v_rcp_f32_e32 v240, v176
	v_rcp_f32_e32 v241, v177
	s_waitcnt vmcnt(30)
	ds_write_b128 v250, v[128:131] offset:0
	ds_write_b128 v250, v[132:135] offset:4224
	ds_write_b128 v250, v[136:139] offset:16896
	ds_write_b128 v250, v[140:143] offset:21120
	s_waitcnt vmcnt(26)
	ds_write_b128 v250, v[144:147] offset:33792
	ds_write_b128 v250, v[148:151] offset:38016
	ds_write_b128 v250, v[152:155] offset:50688
	ds_write_b128 v250, v[156:159] offset:54912
	s_waitcnt vmcnt(22)
	ds_write_b128 v251, v[184:187] offset:0
	ds_write_b128 v251, v[188:191] offset:4224
	ds_write_b128 v251, v[192:195] offset:16896
	ds_write_b128 v251, v[196:199] offset:21120
	s_waitcnt vmcnt(18)
	ds_write_b128 v251, v[200:203] offset:33792
	ds_write_b128 v251, v[204:207] offset:38016
	ds_write_b128 v251, v[208:211] offset:50688
	ds_write_b128 v251, v[212:215] offset:54912
	s_waitcnt lgkmcnt(0)
	s_barrier
	s_mov_b32 s18, 0
	v_mov_b32_e32 v234, v232
	v_add_u32_e32 v235, 16896, v232
	ds_read_b64 v[128:129], v234 offset:0
	ds_read_b64 v[130:131], v234 offset:32
	ds_read_b64 v[132:133], v234 offset:64
	ds_read_b64 v[134:135], v234 offset:96
	ds_read_b64 v[136:137], v234 offset:128
	ds_read_b64 v[138:139], v234 offset:160
	ds_read_b64 v[140:141], v234 offset:192
	ds_read_b64 v[142:143], v234 offset:224
	ds_read_b64 v[144:145], v234 offset:256
	ds_read_b64 v[146:147], v234 offset:288
	ds_read_b64 v[148:149], v234 offset:320
	ds_read_b64 v[150:151], v234 offset:352
